# ffnfix_local: loads of the three passes issued together (one memory round trip instead of three before the down GEMM)
# speedup vs baseline: 1.0025x; 1.0025x over previous
.LBB0_224:
	s_mov_b64 s[16:17], 0x800
	v_lshl_add_u64 v[26:27], v[4:5], 0, s[16:17]
	v_lshl_add_u64 v[28:29], v[26:27], 0, s[16:17]
	v_lshl_add_u64 v[6:7], s[10:11], 0, v[2:3]
	v_add_co_u32_e32 v8, vcc, 0x1f000000, v6
	v_lshl_add_u64 v[10:11], s[8:9], 0, v[2:3]
	s_nop 0
	v_addc_co_u32_e32 v9, vcc, 0, v7, vcc
	v_add_co_u32_e32 v6, vcc, 0x1f002000, v6
	v_lshl_add_u64 v[18:19], s[6:7], 0, v[2:3]
	s_nop 0
	v_addc_co_u32_e32 v7, vcc, 0, v7, vcc
	v_add_co_u32_e32 v12, vcc, 0x1f160000, v10
	global_load_dwordx2 v[8:9], v[8:9], off
	s_nop 0
	v_addc_co_u32_e32 v13, vcc, 0, v11, vcc
	v_add_co_u32_e32 v14, vcc, 0x1f165000, v10
	global_load_dwordx2 v[6:7], v[6:7], off offset:3072
	s_nop 0
	v_addc_co_u32_e32 v15, vcc, 0, v11, vcc
	v_add_co_u32_e32 v16, vcc, 0x1f162000, v10
	global_load_dwordx2 v[20:21], v[18:19], off
	s_nop 0
	v_addc_co_u32_e32 v17, vcc, 0, v11, vcc
	v_add_co_u32_e32 v10, vcc, 0x1f168000, v10
	global_load_dwordx2 v[12:13], v[12:13], off
	s_nop 0
	v_addc_co_u32_e32 v11, vcc, 0, v11, vcc
	v_add_co_u32_e32 v22, vcc, 0x2000, v18
	global_load_dwordx2 v[14:15], v[14:15], off offset:2048
	s_nop 0
	v_addc_co_u32_e32 v23, vcc, 0, v19, vcc
	global_load_dwordx2 v[22:23], v[22:23], off offset:3072
	v_add_co_u32_e32 v18, vcc, 0x5000, v18
	global_load_dwordx2 v[16:17], v[16:17], off offset:3072
	s_nop 0
	v_addc_co_u32_e32 v19, vcc, 0, v19, vcc
	global_load_dwordx2 v[18:19], v[18:19], off offset:2048
	s_add_u32 s8, s8, 0x1000
	global_load_dwordx2 v[10:11], v[10:11], off offset:1024
	s_addc_u32 s9, s9, 0
	s_movk_i32 s15, 0xea00
	s_add_u32 s10, s10, 0x1000
	s_addc_u32 s11, s11, 0
	v_add_u32_e32 v0, 0x400, v0
	s_add_u32 s6, s6, 0x1000
	s_addc_u32 s7, s7, 0
	v_lshl_add_u64 v[32:33], s[10:11], 0, v[2:3]
	v_add_co_u32_e32 v34, vcc, 0x1f000000, v32
	v_lshl_add_u64 v[36:37], s[8:9], 0, v[2:3]
	s_nop 0
	v_addc_co_u32_e32 v35, vcc, 0, v33, vcc
	v_add_co_u32_e32 v32, vcc, 0x1f002000, v32
	v_lshl_add_u64 v[44:45], s[6:7], 0, v[2:3]
	s_nop 0
	v_addc_co_u32_e32 v33, vcc, 0, v33, vcc
	v_add_co_u32_e32 v38, vcc, 0x1f160000, v36
	global_load_dwordx2 v[34:35], v[34:35], off
	s_nop 0
	v_addc_co_u32_e32 v39, vcc, 0, v37, vcc
	v_add_co_u32_e32 v40, vcc, 0x1f165000, v36
	global_load_dwordx2 v[32:33], v[32:33], off offset:3072
	s_nop 0
	v_addc_co_u32_e32 v41, vcc, 0, v37, vcc
	v_add_co_u32_e32 v42, vcc, 0x1f162000, v36
	global_load_dwordx2 v[46:47], v[44:45], off
	s_nop 0
	v_addc_co_u32_e32 v43, vcc, 0, v37, vcc
	v_add_co_u32_e32 v36, vcc, 0x1f168000, v36
	global_load_dwordx2 v[38:39], v[38:39], off
	s_nop 0
	v_addc_co_u32_e32 v37, vcc, 0, v37, vcc
	v_add_co_u32_e32 v48, vcc, 0x2000, v44
	global_load_dwordx2 v[40:41], v[40:41], off offset:2048
	s_nop 0
	v_addc_co_u32_e32 v49, vcc, 0, v45, vcc
	global_load_dwordx2 v[48:49], v[48:49], off offset:3072
	v_add_co_u32_e32 v44, vcc, 0x5000, v44
	global_load_dwordx2 v[42:43], v[42:43], off offset:3072
	s_nop 0
	v_addc_co_u32_e32 v45, vcc, 0, v45, vcc
	global_load_dwordx2 v[44:45], v[44:45], off offset:2048
	s_add_u32 s8, s8, 0x1000
	global_load_dwordx2 v[36:37], v[36:37], off offset:1024
	s_addc_u32 s9, s9, 0
	s_movk_i32 s15, 0xea00
	s_add_u32 s10, s10, 0x1000
	s_addc_u32 s11, s11, 0
	v_add_u32_e32 v0, 0x400, v0
	s_add_u32 s6, s6, 0x1000
	s_addc_u32 s7, s7, 0
	s_mov_b64 s[18:19], exec
	s_movk_i32 s15, 0x6ff
	v_cmp_ge_i32_e32 vcc, s15, v0
	s_and_b64 exec, exec, vcc
	v_lshl_add_u64 v[58:59], s[10:11], 0, v[2:3]
	v_add_co_u32_e32 v60, vcc, 0x1f000000, v58
	v_lshl_add_u64 v[62:63], s[8:9], 0, v[2:3]
	s_nop 0
	v_addc_co_u32_e32 v61, vcc, 0, v59, vcc
	v_add_co_u32_e32 v58, vcc, 0x1f002000, v58
	v_lshl_add_u64 v[70:71], s[6:7], 0, v[2:3]
	s_nop 0
	v_addc_co_u32_e32 v59, vcc, 0, v59, vcc
	v_add_co_u32_e32 v64, vcc, 0x1f160000, v62
	global_load_dwordx2 v[60:61], v[60:61], off
	s_nop 0
	v_addc_co_u32_e32 v65, vcc, 0, v63, vcc
	v_add_co_u32_e32 v66, vcc, 0x1f165000, v62
	global_load_dwordx2 v[58:59], v[58:59], off offset:3072
	s_nop 0
	v_addc_co_u32_e32 v67, vcc, 0, v63, vcc
	v_add_co_u32_e32 v68, vcc, 0x1f162000, v62
	global_load_dwordx2 v[72:73], v[70:71], off
	s_nop 0
	v_addc_co_u32_e32 v69, vcc, 0, v63, vcc
	v_add_co_u32_e32 v62, vcc, 0x1f168000, v62
	global_load_dwordx2 v[64:65], v[64:65], off
	s_nop 0
	v_addc_co_u32_e32 v63, vcc, 0, v63, vcc
	v_add_co_u32_e32 v74, vcc, 0x2000, v70
	global_load_dwordx2 v[66:67], v[66:67], off offset:2048
	s_nop 0
	v_addc_co_u32_e32 v75, vcc, 0, v71, vcc
	global_load_dwordx2 v[74:75], v[74:75], off offset:3072
	v_add_co_u32_e32 v70, vcc, 0x5000, v70
	global_load_dwordx2 v[68:69], v[68:69], off offset:3072
	s_nop 0
	v_addc_co_u32_e32 v71, vcc, 0, v71, vcc
	global_load_dwordx2 v[70:71], v[70:71], off offset:2048
	s_add_u32 s8, s8, 0x1000
	global_load_dwordx2 v[62:63], v[62:63], off offset:1024
	s_addc_u32 s9, s9, 0
	s_movk_i32 s15, 0xea00
	s_add_u32 s10, s10, 0x1000
	s_addc_u32 s11, s11, 0
	v_add_u32_e32 v0, 0x400, v0
	s_add_u32 s6, s6, 0x1000
	s_addc_u32 s7, s7, 0
	s_waitcnt vmcnt(0)
	v_mul_f32_e32 v76, v58, v74
	v_fmac_f32_e32 v76, v60, v72
	v_mul_f32_e32 v60, v64, v74
	v_fmac_f32_e32 v60, v58, v72
	v_fmac_f32_e32 v76, v64, v70
	v_mul_f32_e32 v58, 0xbfb8aa3b, v76
	v_exp_f32_e32 v58, v58
	v_fmac_f32_e32 v60, v66, v70
	v_add_f32_e32 v58, 1.0, v58
	v_div_scale_f32 v64, s[16:17], v58, v58, v76
	v_rcp_f32_e32 v66, v64
	s_nop 0
	v_fma_f32 v70, -v64, v66, 1.0
	v_fmac_f32_e32 v66, v70, v66
	v_div_scale_f32 v70, vcc, v76, v58, v76
	v_mul_f32_e32 v72, v70, v66
	v_fma_f32 v74, -v64, v72, v70
	v_fmac_f32_e32 v72, v74, v66
	v_fma_f32 v64, -v64, v72, v70
	v_div_fmas_f32 v64, v64, v66, v72
	v_div_fixup_f32 v58, v64, v58, v76
	v_mul_f32_e32 v64, 0xbfb8aa3b, v60
	v_exp_f32_e32 v64, v64
	v_mul_f32_e32 v58, v68, v58
	v_add_f32_e32 v64, 1.0, v64
	v_div_scale_f32 v66, s[16:17], v64, v64, v60
	v_rcp_f32_e32 v68, v66
	s_nop 0
	v_fma_f32 v70, -v66, v68, 1.0
	v_fmac_f32_e32 v68, v70, v68
	v_div_scale_f32 v70, vcc, v60, v64, v60
	v_mul_f32_e32 v72, v70, v68
	v_fma_f32 v74, -v66, v72, v70
	v_fmac_f32_e32 v72, v74, v68
	v_fma_f32 v66, -v66, v72, v70
	v_div_fmas_f32 v66, v66, v68, v72
	v_div_fixup_f32 v60, v66, v64, v60
	v_mul_f32_e32 v60, v62, v60
	v_mul_f32_e32 v62, v59, v75
	v_fmac_f32_e32 v62, v61, v73
	v_fmac_f32_e32 v62, v65, v71
	v_mul_f32_e32 v61, v65, v75
	v_fmac_f32_e32 v61, v59, v73
	v_mul_f32_e32 v59, 0xbfb8aa3b, v62
	v_exp_f32_e32 v59, v59
	v_fmac_f32_e32 v61, v67, v71
	v_add_f32_e32 v59, 1.0, v59
	v_div_scale_f32 v64, s[16:17], v59, v59, v62
	v_rcp_f32_e32 v65, v64
	s_nop 0
	v_fma_f32 v66, -v64, v65, 1.0
	v_fmac_f32_e32 v65, v66, v65
	v_div_scale_f32 v66, vcc, v62, v59, v62
	v_mul_f32_e32 v67, v66, v65
	v_fma_f32 v68, -v64, v67, v66
	v_fmac_f32_e32 v67, v68, v65
	v_fma_f32 v64, -v64, v67, v66
	v_div_fmas_f32 v64, v64, v65, v67
	v_div_fixup_f32 v59, v64, v59, v62
	v_mul_f32_e32 v62, 0xbfb8aa3b, v61
	v_exp_f32_e32 v62, v62
	v_mul_f32_e32 v59, v69, v59
	v_add_f32_e32 v62, 1.0, v62
	v_div_scale_f32 v64, s[16:17], v62, v62, v61
	v_rcp_f32_e32 v65, v64
	s_nop 0
	v_fma_f32 v66, -v64, v65, 1.0
	v_fmac_f32_e32 v65, v66, v65
	v_div_scale_f32 v66, vcc, v61, v62, v61
	v_mul_f32_e32 v67, v66, v65
	v_fma_f32 v68, -v64, v67, v66
	v_fmac_f32_e32 v67, v68, v65
	v_fma_f32 v64, -v64, v67, v66
	v_div_fmas_f32 v64, v64, v65, v67
	v_div_fixup_f32 v61, v64, v62, v61
	v_cvt_pk_bf16_f32 v62, v58, v59
	v_add_co_u32_e32 v58, vcc, s15, v28
	s_nop 0
	s_nop 0
	v_addc_co_u32_e32 v59, vcc, -1, v29, vcc
	v_mul_f32_e32 v61, v63, v61
	global_store_dword v[58:59], v62, off
	v_cvt_pk_bf16_f32 v58, v60, v61
	global_store_dword v[28:29], v58, off
	s_mov_b64 exec, s[18:19]
	v_mul_f32_e32 v24, v6, v22
	v_fmac_f32_e32 v24, v8, v20
	v_mul_f32_e32 v8, v12, v22
	v_fmac_f32_e32 v8, v6, v20
	v_fmac_f32_e32 v24, v12, v18
	v_mul_f32_e32 v6, 0xbfb8aa3b, v24
	v_exp_f32_e32 v6, v6
	v_fmac_f32_e32 v8, v14, v18
	v_add_f32_e32 v6, 1.0, v6
	v_div_scale_f32 v12, s[16:17], v6, v6, v24
	v_rcp_f32_e32 v14, v12
	s_nop 0
	v_fma_f32 v18, -v12, v14, 1.0
	v_fmac_f32_e32 v14, v18, v14
	v_div_scale_f32 v18, vcc, v24, v6, v24
	v_mul_f32_e32 v20, v18, v14
	v_fma_f32 v22, -v12, v20, v18
	v_fmac_f32_e32 v20, v22, v14
	v_fma_f32 v12, -v12, v20, v18
	v_div_fmas_f32 v12, v12, v14, v20
	v_div_fixup_f32 v6, v12, v6, v24
	v_mul_f32_e32 v12, 0xbfb8aa3b, v8
	v_exp_f32_e32 v12, v12
	v_mul_f32_e32 v6, v16, v6
	v_add_f32_e32 v12, 1.0, v12
	v_div_scale_f32 v14, s[16:17], v12, v12, v8
	v_rcp_f32_e32 v16, v14
	s_nop 0
	v_fma_f32 v18, -v14, v16, 1.0
	v_fmac_f32_e32 v16, v18, v16
	v_div_scale_f32 v18, vcc, v8, v12, v8
	v_mul_f32_e32 v20, v18, v16
	v_fma_f32 v22, -v14, v20, v18
	v_fmac_f32_e32 v20, v22, v16
	v_fma_f32 v14, -v14, v20, v18
	v_div_fmas_f32 v14, v14, v16, v20
	v_div_fixup_f32 v8, v14, v12, v8
	v_mul_f32_e32 v8, v10, v8
	v_mul_f32_e32 v10, v7, v23
	v_fmac_f32_e32 v10, v9, v21
	v_fmac_f32_e32 v10, v13, v19
	v_mul_f32_e32 v9, v13, v23
	v_fmac_f32_e32 v9, v7, v21
	v_mul_f32_e32 v7, 0xbfb8aa3b, v10
	v_exp_f32_e32 v7, v7
	v_fmac_f32_e32 v9, v15, v19
	v_add_f32_e32 v7, 1.0, v7
	v_div_scale_f32 v12, s[16:17], v7, v7, v10
	v_rcp_f32_e32 v13, v12
	s_nop 0
	v_fma_f32 v14, -v12, v13, 1.0
	v_fmac_f32_e32 v13, v14, v13
	v_div_scale_f32 v14, vcc, v10, v7, v10
	v_mul_f32_e32 v15, v14, v13
	v_fma_f32 v16, -v12, v15, v14
	v_fmac_f32_e32 v15, v16, v13
	v_fma_f32 v12, -v12, v15, v14
	v_div_fmas_f32 v12, v12, v13, v15
	v_div_fixup_f32 v7, v12, v7, v10
	v_mul_f32_e32 v10, 0xbfb8aa3b, v9
	v_exp_f32_e32 v10, v10
	v_mul_f32_e32 v7, v17, v7
	v_add_f32_e32 v10, 1.0, v10
	v_div_scale_f32 v12, s[16:17], v10, v10, v9
	v_rcp_f32_e32 v13, v12
	s_nop 0
	v_fma_f32 v14, -v12, v13, 1.0
	v_fmac_f32_e32 v13, v14, v13
	v_div_scale_f32 v14, vcc, v9, v10, v9
	v_mul_f32_e32 v15, v14, v13
	v_fma_f32 v16, -v12, v15, v14
	v_fmac_f32_e32 v15, v16, v13
	v_fma_f32 v12, -v12, v15, v14
	v_div_fmas_f32 v12, v12, v13, v15
	v_div_fixup_f32 v9, v12, v10, v9
	v_cvt_pk_bf16_f32 v10, v6, v7
	v_add_co_u32_e32 v6, vcc, s15, v4
	s_nop 0
	s_nop 0
	v_addc_co_u32_e32 v7, vcc, -1, v5, vcc
	v_mul_f32_e32 v9, v11, v9
	global_store_dword v[6:7], v10, off
	v_cvt_pk_bf16_f32 v6, v8, v9
	global_store_dword v[4:5], v6, off
	v_mul_f32_e32 v50, v32, v48
	v_fmac_f32_e32 v50, v34, v46
	v_mul_f32_e32 v34, v38, v48
	v_fmac_f32_e32 v34, v32, v46
	v_fmac_f32_e32 v50, v38, v44
	v_mul_f32_e32 v32, 0xbfb8aa3b, v50
	v_exp_f32_e32 v32, v32
	v_fmac_f32_e32 v34, v40, v44
	v_add_f32_e32 v32, 1.0, v32
	v_div_scale_f32 v38, s[16:17], v32, v32, v50
	v_rcp_f32_e32 v40, v38
	s_nop 0
	v_fma_f32 v44, -v38, v40, 1.0
	v_fmac_f32_e32 v40, v44, v40
	v_div_scale_f32 v44, vcc, v50, v32, v50
	v_mul_f32_e32 v46, v44, v40
	v_fma_f32 v48, -v38, v46, v44
	v_fmac_f32_e32 v46, v48, v40
	v_fma_f32 v38, -v38, v46, v44
	v_div_fmas_f32 v38, v38, v40, v46
	v_div_fixup_f32 v32, v38, v32, v50
	v_mul_f32_e32 v38, 0xbfb8aa3b, v34
	v_exp_f32_e32 v38, v38
	v_mul_f32_e32 v32, v42, v32
	v_add_f32_e32 v38, 1.0, v38
	v_div_scale_f32 v40, s[16:17], v38, v38, v34
	v_rcp_f32_e32 v42, v40
	s_nop 0
	v_fma_f32 v44, -v40, v42, 1.0
	v_fmac_f32_e32 v42, v44, v42
	v_div_scale_f32 v44, vcc, v34, v38, v34
	v_mul_f32_e32 v46, v44, v42
	v_fma_f32 v48, -v40, v46, v44
	v_fmac_f32_e32 v46, v48, v42
	v_fma_f32 v40, -v40, v46, v44
	v_div_fmas_f32 v40, v40, v42, v46
	v_div_fixup_f32 v34, v40, v38, v34
	v_mul_f32_e32 v34, v36, v34
	v_mul_f32_e32 v36, v33, v49
	v_fmac_f32_e32 v36, v35, v47
	v_fmac_f32_e32 v36, v39, v45
	v_mul_f32_e32 v35, v39, v49
	v_fmac_f32_e32 v35, v33, v47
	v_mul_f32_e32 v33, 0xbfb8aa3b, v36
	v_exp_f32_e32 v33, v33
	v_fmac_f32_e32 v35, v41, v45
	v_add_f32_e32 v33, 1.0, v33
	v_div_scale_f32 v38, s[16:17], v33, v33, v36
	v_rcp_f32_e32 v39, v38
	s_nop 0
	v_fma_f32 v40, -v38, v39, 1.0
	v_fmac_f32_e32 v39, v40, v39
	v_div_scale_f32 v40, vcc, v36, v33, v36
	v_mul_f32_e32 v41, v40, v39
	v_fma_f32 v42, -v38, v41, v40
	v_fmac_f32_e32 v41, v42, v39
	v_fma_f32 v38, -v38, v41, v40
	v_div_fmas_f32 v38, v38, v39, v41
	v_div_fixup_f32 v33, v38, v33, v36
	v_mul_f32_e32 v36, 0xbfb8aa3b, v35
	v_exp_f32_e32 v36, v36
	v_mul_f32_e32 v33, v43, v33
	v_add_f32_e32 v36, 1.0, v36
	v_div_scale_f32 v38, s[16:17], v36, v36, v35
	v_rcp_f32_e32 v39, v38
	s_nop 0
	v_fma_f32 v40, -v38, v39, 1.0
	v_fmac_f32_e32 v39, v40, v39
	v_div_scale_f32 v40, vcc, v35, v36, v35
	v_mul_f32_e32 v41, v40, v39
	v_fma_f32 v42, -v38, v41, v40
	v_fmac_f32_e32 v41, v42, v39
	v_fma_f32 v38, -v38, v41, v40
	v_div_fmas_f32 v38, v38, v39, v41
	v_div_fixup_f32 v35, v38, v36, v35
	v_cvt_pk_bf16_f32 v36, v32, v33
	v_add_co_u32_e32 v32, vcc, s15, v26
	s_nop 0
	s_nop 0
	v_addc_co_u32_e32 v33, vcc, -1, v27, vcc
	v_mul_f32_e32 v35, v37, v35
	global_store_dword v[32:33], v36, off
	v_cvt_pk_bf16_f32 v32, v34, v35
	global_store_dword v[26:27], v32, off
	s_movk_i32 s15, 0x6ff
	s_mov_b64 s[16:17], 0x800
	s_mov_b64 s[18:19], -1
